# prologue x_half: gate-weight bf16 fragments built once per workgroup in LDS, x streamed in 1 KB-per-row bursts, stores batched
# baseline (speedup 1.0000x reference)
; __device__ __forceinline__ unsigned cvt_pk_bf16(float lo, float hi) { unsigned r; asm volatile("v_cvt_pk_bf16_f32 %0, %1, %2" : "=v"(r) : "v"(lo), "v"(hi)); return r; }
; __device__ __forceinline__ void x_half(KA a, int grp, int half, int lane, f32x4& acc, float& ss) {
;     ...
;     const int row0 = grp * 16, r = lane & 15, quad = lane >> 4, kbase = half * 1024;
;     const float* xr = x + (size_t)(row0 + r) * D_ + quad * 8 + kbase; bf16_t* br = XB + (size_t)(row0 + r) * D_ + quad * 8 + kbase;
;     const float* wp = W + (size_t)(kbase + quad * 8) * 6160 + 6144 + r; const float* gp = gmix + kbase + quad * 8;
;     acc = (f32x4){0.f, 0.f, 0.f, 0.f}; ss = 0.f;
; #pragma unroll 4
;     for (int k0 = 0; k0 < 1024; k0 += 32) {
;         const f32x4 a0 = *(const f32x4*)(xr + k0), a1 = *(const f32x4*)(xr + k0 + 4);
;         ss += (a0[0] * a0[0] + a0[1] * a0[1]) + (a0[2] * a0[2] + a0[3] * a0[3]) + (a1[0] * a1[0] + a1[1] * a1[1]) + (a1[2] * a1[2] + a1[3] * a1[3]);
;         u32x4 aw; aw.x = cvt_pk_bf16(a0[0], a0[1]); aw.y = cvt_pk_bf16(a0[2], a0[3]); aw.z = cvt_pk_bf16(a1[0], a1[1]); aw.w = cvt_pk_bf16(a1[2], a1[3]);
;         *(u32x4*)(br + k0) = aw;
;         const f32x4 g0 = *(const f32x4*)(gp + k0), g1 = *(const f32x4*)(gp + k0 + 4);
;         const float* w = wp + (size_t)k0 * 6160;
;         u32x4 bw; bw.x = cvt_pk_bf16(w[0] * g0[0], w[6160] * g0[1]); bw.y = cvt_pk_bf16(w[2 * 6160] * g0[2], w[3 * 6160] * g0[3]);
;         bw.z = cvt_pk_bf16(w[4 * 6160] * g1[0], w[5 * 6160] * g1[1]); bw.w = cvt_pk_bf16(w[6 * 6160] * g1[2], w[7 * 6160] * g1[3]);
;         acc = __builtin_amdgcn_mfma_f32_16x16x32_bf16(__builtin_bit_cast(bf16x8, aw), __builtin_bit_cast(bf16x8, bw), acc, 0, 0, 0);
;     }
.LBB0_9:
	v_ashrrev_i32_e32 v67, 31, v66
	v_lshlrev_b64 v[4:5], 13, v[66:67]
	v_lshlrev_b64 v[6:7], 12, v[66:67]
	v_lshl_add_u64 v[4:5], s[8:9], 0, v[4:5]
	v_lshl_add_u64 v[70:71], v[68:69], 0, v[6:7]
	s_movk_i32 s71, 0xffe0
	s_mov_b64 s[26:27], s[10:11]
	v_mov_b64_e32 v[72:73], v[62:63]
	v_mov_b32_e32 v2, 0
	v_mov_b32_e32 v6, 0
	v_mov_b32_e32 v7, v3
	v_mov_b32_e32 v8, v3
	v_mov_b32_e32 v9, v3
	s_load_dwordx2 s[28:29], s[92:93], 0x20
	v_lshl_add_u64 v[4:5], v[4:5], 0, v[64:65]
	v_lshrrev_b32_e32 v26, 4, v167
	v_mul_u32_u24_e32 v26, 0x30200, v26
	v_lshl_add_u32 v26, v79, 2, v26
	v_add_u32_e32 v27, 0x6040, v26
	v_add_u32_e32 v28, 0xc080, v26
	v_add_u32_e32 v29, 0x120c0, v26
	v_add_u32_e32 v30, 0x18100, v26
	v_add_u32_e32 v31, 0x1e140, v26
	v_add_u32_e32 v32, 0x24180, v26
	v_add_u32_e32 v33, 0x2a1c0, v26
	s_lshr_b32 s25, s46, 2
	s_lshl_b32 s30, s25, 15
	s_add_i32 s30, s30, 0x10000
	v_lshl_add_u32 v34, v167, 4, s30
	s_mul_i32 s25, s25, 0x1810000
	s_add_i32 s25, s25, 0x6000
	s_and_b32 s31, s46, 3
	s_mul_i32 s33, s31, 0x604000
	s_add_i32 s25, s25, s33
	s_lshl_b32 s33, s31, 10
	s_waitcnt vmcnt(0) lgkmcnt(0)
	s_add_u32 s28, s28, s25
	s_addc_u32 s29, s29, 0
	s_add_u32 s34, s26, s33
	s_addc_u32 s35, s27, 0
	s_lshl_b32 s33, s31, 13
	v_add_u32_e32 v35, s33, v34
	global_load_dwordx4 v[100:103], v64, s[34:35]
	global_load_dwordx4 v[104:107], v64, s[34:35] offset:16
	global_load_dword v108, v26, s[28:29]
	global_load_dword v109, v27, s[28:29]
	global_load_dword v110, v28, s[28:29]
	global_load_dword v111, v29, s[28:29]
	global_load_dword v112, v30, s[28:29]
	global_load_dword v113, v31, s[28:29]
	global_load_dword v114, v32, s[28:29]
	global_load_dword v115, v33, s[28:29]
	s_add_u32 s28, s28, 0xc0800
	s_addc_u32 s29, s29, 0
	global_load_dwordx4 v[116:119], v64, s[34:35] offset:128
	global_load_dwordx4 v[120:123], v64, s[34:35] offset:144
	global_load_dword v124, v26, s[28:29]
	global_load_dword v125, v27, s[28:29]
	global_load_dword v126, v28, s[28:29]
	global_load_dword v127, v29, s[28:29]
	global_load_dword v128, v30, s[28:29]
	global_load_dword v129, v31, s[28:29]
	global_load_dword v130, v32, s[28:29]
	global_load_dword v131, v33, s[28:29]
	s_add_u32 s28, s28, 0xc0800
	s_addc_u32 s29, s29, 0
	global_load_dwordx4 v[132:135], v64, s[34:35] offset:256
	global_load_dwordx4 v[136:139], v64, s[34:35] offset:272
	global_load_dword v140, v26, s[28:29]
	global_load_dword v141, v27, s[28:29]
	global_load_dword v142, v28, s[28:29]
	global_load_dword v143, v29, s[28:29]
	global_load_dword v144, v30, s[28:29]
	global_load_dword v145, v31, s[28:29]
	global_load_dword v146, v32, s[28:29]
	global_load_dword v147, v33, s[28:29]
	s_add_u32 s28, s28, 0xc0800
	s_addc_u32 s29, s29, 0
	global_load_dwordx4 v[148:151], v64, s[34:35] offset:384
	global_load_dwordx4 v[152:155], v64, s[34:35] offset:400
	global_load_dword v156, v26, s[28:29]
	global_load_dword v157, v27, s[28:29]
	global_load_dword v158, v28, s[28:29]
	global_load_dword v159, v29, s[28:29]
	global_load_dword v160, v30, s[28:29]
	global_load_dword v161, v31, s[28:29]
	global_load_dword v162, v32, s[28:29]
	global_load_dword v163, v33, s[28:29]
	s_add_u32 s28, s28, 0xc0800
	s_addc_u32 s29, s29, 0
	s_waitcnt vmcnt(0)
	v_mul_f32_e32 v108, v108, v100
	v_mul_f32_e32 v109, v109, v101
	v_mul_f32_e32 v110, v110, v102
	v_mul_f32_e32 v111, v111, v103
	v_mul_f32_e32 v112, v112, v104
	v_mul_f32_e32 v113, v113, v105
	v_mul_f32_e32 v114, v114, v106
	v_mul_f32_e32 v115, v115, v107
	v_cvt_pk_bf16_f32 v100, v108, v109
	v_cvt_pk_bf16_f32 v101, v110, v111
	v_cvt_pk_bf16_f32 v102, v112, v113
	v_cvt_pk_bf16_f32 v103, v114, v115
	ds_write_b128 v35, v[100:103] offset:0
	v_mul_f32_e32 v124, v124, v116
	v_mul_f32_e32 v125, v125, v117
	v_mul_f32_e32 v126, v126, v118
	v_mul_f32_e32 v127, v127, v119
	v_mul_f32_e32 v128, v128, v120
	v_mul_f32_e32 v129, v129, v121
	v_mul_f32_e32 v130, v130, v122
	v_mul_f32_e32 v131, v131, v123
	v_cvt_pk_bf16_f32 v116, v124, v125
	v_cvt_pk_bf16_f32 v117, v126, v127
	v_cvt_pk_bf16_f32 v118, v128, v129
	v_cvt_pk_bf16_f32 v119, v130, v131
	ds_write_b128 v35, v[116:119] offset:1024
	v_mul_f32_e32 v140, v140, v132
	v_mul_f32_e32 v141, v141, v133
	v_mul_f32_e32 v142, v142, v134
	v_mul_f32_e32 v143, v143, v135
	v_mul_f32_e32 v144, v144, v136
	v_mul_f32_e32 v145, v145, v137
	v_mul_f32_e32 v146, v146, v138
	v_mul_f32_e32 v147, v147, v139
	v_cvt_pk_bf16_f32 v132, v140, v141
	v_cvt_pk_bf16_f32 v133, v142, v143
	v_cvt_pk_bf16_f32 v134, v144, v145
	v_cvt_pk_bf16_f32 v135, v146, v147
	ds_write_b128 v35, v[132:135] offset:2048
	v_mul_f32_e32 v156, v156, v148
	v_mul_f32_e32 v157, v157, v149
	v_mul_f32_e32 v158, v158, v150
	v_mul_f32_e32 v159, v159, v151
	v_mul_f32_e32 v160, v160, v152
	v_mul_f32_e32 v161, v161, v153
	v_mul_f32_e32 v162, v162, v154
	v_mul_f32_e32 v163, v163, v155
	v_cvt_pk_bf16_f32 v148, v156, v157
	v_cvt_pk_bf16_f32 v149, v158, v159
	v_cvt_pk_bf16_f32 v150, v160, v161
	v_cvt_pk_bf16_f32 v151, v162, v163
	ds_write_b128 v35, v[148:151] offset:3072
	global_load_dwordx4 v[100:103], v64, s[34:35] offset:512
	global_load_dwordx4 v[104:107], v64, s[34:35] offset:528
	global_load_dword v108, v26, s[28:29]
	global_load_dword v109, v27, s[28:29]
	global_load_dword v110, v28, s[28:29]
	global_load_dword v111, v29, s[28:29]
	global_load_dword v112, v30, s[28:29]
	global_load_dword v113, v31, s[28:29]
	global_load_dword v114, v32, s[28:29]
	global_load_dword v115, v33, s[28:29]
	s_add_u32 s28, s28, 0xc0800
	s_addc_u32 s29, s29, 0
	global_load_dwordx4 v[116:119], v64, s[34:35] offset:640
	global_load_dwordx4 v[120:123], v64, s[34:35] offset:656
	global_load_dword v124, v26, s[28:29]
	global_load_dword v125, v27, s[28:29]
	global_load_dword v126, v28, s[28:29]
	global_load_dword v127, v29, s[28:29]
	global_load_dword v128, v30, s[28:29]
	global_load_dword v129, v31, s[28:29]
	global_load_dword v130, v32, s[28:29]
	global_load_dword v131, v33, s[28:29]
	s_add_u32 s28, s28, 0xc0800
	s_addc_u32 s29, s29, 0
	global_load_dwordx4 v[132:135], v64, s[34:35] offset:768
	global_load_dwordx4 v[136:139], v64, s[34:35] offset:784
	global_load_dword v140, v26, s[28:29]
	global_load_dword v141, v27, s[28:29]
	global_load_dword v142, v28, s[28:29]
	global_load_dword v143, v29, s[28:29]
	global_load_dword v144, v30, s[28:29]
	global_load_dword v145, v31, s[28:29]
	global_load_dword v146, v32, s[28:29]
	global_load_dword v147, v33, s[28:29]
	s_add_u32 s28, s28, 0xc0800
	s_addc_u32 s29, s29, 0
	global_load_dwordx4 v[148:151], v64, s[34:35] offset:896
	global_load_dwordx4 v[152:155], v64, s[34:35] offset:912
	global_load_dword v156, v26, s[28:29]
	global_load_dword v157, v27, s[28:29]
	global_load_dword v158, v28, s[28:29]
	global_load_dword v159, v29, s[28:29]
	global_load_dword v160, v30, s[28:29]
	global_load_dword v161, v31, s[28:29]
	global_load_dword v162, v32, s[28:29]
	global_load_dword v163, v33, s[28:29]
	s_add_u32 s28, s28, 0xc0800
	s_addc_u32 s29, s29, 0
	s_waitcnt vmcnt(0)
; __device__ __forceinline__ unsigned cvt_pk_bf16(float lo, float hi) { unsigned r; asm volatile("v_cvt_pk_bf16_f32 %0, %1, %2" : "=v"(r) : "v"(lo), "v"(hi)); return r; }
; __device__ __forceinline__ void x_half(KA a, int grp, int half, int lane, f32x4& acc, float& ss) {
;     ...
;     const int row0 = grp * 16, r = lane & 15, quad = lane >> 4, kbase = half * 1024;
;     const float* xr = x + (size_t)(row0 + r) * D_ + quad * 8 + kbase; bf16_t* br = XB + (size_t)(row0 + r) * D_ + quad * 8 + kbase;
;     const float* wp = W + (size_t)(kbase + quad * 8) * 6160 + 6144 + r; const float* gp = gmix + kbase + quad * 8;
;     acc = (f32x4){0.f, 0.f, 0.f, 0.f}; ss = 0.f;
; #pragma unroll 4
;     for (int k0 = 0; k0 < 1024; k0 += 32) {
;         const f32x4 a0 = *(const f32x4*)(xr + k0), a1 = *(const f32x4*)(xr + k0 + 4);
;         ss += (a0[0] * a0[0] + a0[1] * a0[1]) + (a0[2] * a0[2] + a0[3] * a0[3]) + (a1[0] * a1[0] + a1[1] * a1[1]) + (a1[2] * a1[2] + a1[3] * a1[3]);
;         u32x4 aw; aw.x = cvt_pk_bf16(a0[0], a0[1]); aw.y = cvt_pk_bf16(a0[2], a0[3]); aw.z = cvt_pk_bf16(a1[0], a1[1]); aw.w = cvt_pk_bf16(a1[2], a1[3]);
;         *(u32x4*)(br + k0) = aw;
;         const f32x4 g0 = *(const f32x4*)(gp + k0), g1 = *(const f32x4*)(gp + k0 + 4);
;         const float* w = wp + (size_t)k0 * 6160;
;         u32x4 bw; bw.x = cvt_pk_bf16(w[0] * g0[0], w[6160] * g0[1]); bw.y = cvt_pk_bf16(w[2 * 6160] * g0[2], w[3 * 6160] * g0[3]);
;         bw.z = cvt_pk_bf16(w[4 * 6160] * g1[0], w[5 * 6160] * g1[1]); bw.w = cvt_pk_bf16(w[6 * 6160] * g1[2], w[7 * 6160] * g1[3]);
;         acc = __builtin_amdgcn_mfma_f32_16x16x32_bf16(__builtin_bit_cast(bf16x8, aw), __builtin_bit_cast(bf16x8, bw), acc, 0, 0, 0);
;     }
	v_mul_f32_e32 v108, v108, v100
	v_mul_f32_e32 v109, v109, v101
	v_mul_f32_e32 v110, v110, v102
	v_mul_f32_e32 v111, v111, v103
	v_mul_f32_e32 v112, v112, v104
	v_mul_f32_e32 v113, v113, v105
	v_mul_f32_e32 v114, v114, v106
	v_mul_f32_e32 v115, v115, v107
	v_cvt_pk_bf16_f32 v100, v108, v109
	v_cvt_pk_bf16_f32 v101, v110, v111
	v_cvt_pk_bf16_f32 v102, v112, v113
	v_cvt_pk_bf16_f32 v103, v114, v115
	ds_write_b128 v35, v[100:103] offset:4096
	v_mul_f32_e32 v124, v124, v116
	v_mul_f32_e32 v125, v125, v117
	v_mul_f32_e32 v126, v126, v118
	v_mul_f32_e32 v127, v127, v119
	v_mul_f32_e32 v128, v128, v120
	v_mul_f32_e32 v129, v129, v121
	v_mul_f32_e32 v130, v130, v122
	v_mul_f32_e32 v131, v131, v123
	v_cvt_pk_bf16_f32 v116, v124, v125
	v_cvt_pk_bf16_f32 v117, v126, v127
	v_cvt_pk_bf16_f32 v118, v128, v129
	v_cvt_pk_bf16_f32 v119, v130, v131
	ds_write_b128 v35, v[116:119] offset:5120
	v_mul_f32_e32 v140, v140, v132
	v_mul_f32_e32 v141, v141, v133
	v_mul_f32_e32 v142, v142, v134
	v_mul_f32_e32 v143, v143, v135
	v_mul_f32_e32 v144, v144, v136
	v_mul_f32_e32 v145, v145, v137
	v_mul_f32_e32 v146, v146, v138
	v_mul_f32_e32 v147, v147, v139
	v_cvt_pk_bf16_f32 v132, v140, v141
	v_cvt_pk_bf16_f32 v133, v142, v143
	v_cvt_pk_bf16_f32 v134, v144, v145
	v_cvt_pk_bf16_f32 v135, v146, v147
	ds_write_b128 v35, v[132:135] offset:6144
	v_mul_f32_e32 v156, v156, v148
	v_mul_f32_e32 v157, v157, v149
	v_mul_f32_e32 v158, v158, v150
	v_mul_f32_e32 v159, v159, v151
	v_mul_f32_e32 v160, v160, v152
	v_mul_f32_e32 v161, v161, v153
	v_mul_f32_e32 v162, v162, v154
	v_mul_f32_e32 v163, v163, v155
	v_cvt_pk_bf16_f32 v148, v156, v157
	v_cvt_pk_bf16_f32 v149, v158, v159
	v_cvt_pk_bf16_f32 v150, v160, v161
	v_cvt_pk_bf16_f32 v151, v162, v163
	ds_write_b128 v35, v[148:151] offset:7168
	s_waitcnt lgkmcnt(0)
	s_barrier
	global_load_dwordx4 v[100:103], v[4:5], off
	global_load_dwordx4 v[104:107], v[4:5], off offset:16
	global_load_dwordx4 v[108:111], v[4:5], off offset:128
	global_load_dwordx4 v[112:115], v[4:5], off offset:144
	global_load_dwordx4 v[116:119], v[4:5], off offset:256
	global_load_dwordx4 v[120:123], v[4:5], off offset:272
	global_load_dwordx4 v[124:127], v[4:5], off offset:384
	global_load_dwordx4 v[128:131], v[4:5], off offset:400
	global_load_dwordx4 v[132:135], v[4:5], off offset:512
	global_load_dwordx4 v[136:139], v[4:5], off offset:528
	global_load_dwordx4 v[140:143], v[4:5], off offset:640
	global_load_dwordx4 v[144:147], v[4:5], off offset:656
	global_load_dwordx4 v[148:151], v[4:5], off offset:768
	global_load_dwordx4 v[152:155], v[4:5], off offset:784
	global_load_dwordx4 v[156:159], v[4:5], off offset:896
	global_load_dwordx4 v[160:163], v[4:5], off offset:912
	global_load_dwordx4 v[168:171], v[4:5], off offset:1024
	global_load_dwordx4 v[172:175], v[4:5], off offset:1040
	global_load_dwordx4 v[176:179], v[4:5], off offset:1152
	global_load_dwordx4 v[180:183], v[4:5], off offset:1168
	global_load_dwordx4 v[184:187], v[4:5], off offset:1280
	global_load_dwordx4 v[188:191], v[4:5], off offset:1296
	global_load_dwordx4 v[192:195], v[4:5], off offset:1408
	global_load_dwordx4 v[196:199], v[4:5], off offset:1424
	global_load_dwordx4 v[200:203], v[4:5], off offset:1536
	global_load_dwordx4 v[204:207], v[4:5], off offset:1552
	global_load_dwordx4 v[208:211], v[4:5], off offset:1664
	global_load_dwordx4 v[212:215], v[4:5], off offset:1680
	global_load_dwordx4 v[216:219], v[4:5], off offset:1792
	global_load_dwordx4 v[220:223], v[4:5], off offset:1808
	global_load_dwordx4 v[224:227], v[4:5], off offset:1920
	global_load_dwordx4 v[228:231], v[4:5], off offset:1936
	s_waitcnt vmcnt(30)
	ds_read_b128 v[14:17], v34
	v_cvt_pk_bf16_f32 v36, v100, v101
	v_cvt_pk_bf16_f32 v37, v102, v103
	v_cvt_pk_bf16_f32 v38, v104, v105
	v_cvt_pk_bf16_f32 v39, v106, v107
	v_mul_f32_e32 v100, v100, v100
	v_mul_f32_e32 v101, v101, v101
	v_mul_f32_e32 v102, v102, v102
	v_mul_f32_e32 v103, v103, v103
	v_mul_f32_e32 v104, v104, v104
	v_mul_f32_e32 v105, v105, v105
	v_mul_f32_e32 v106, v106, v106
	v_mul_f32_e32 v107, v107, v107
	v_add_f32_e32 v100, v100, v101
	v_add_f32_e32 v102, v102, v103
	v_add_f32_e32 v100, v100, v102
	v_add_f32_e32 v104, v104, v105
	v_add_f32_e32 v100, v100, v104
	v_add_f32_e32 v106, v106, v107
	v_add_f32_e32 v100, v100, v106
	v_add_f32_e32 v2, v2, v100
	s_waitcnt lgkmcnt(0)
	v_mfma_f32_16x16x32_bf16 v[6:9], v[36:39], v[14:17], v[6:9]
	s_waitcnt vmcnt(28)
	ds_read_b128 v[22:25], v34 offset:1024
	v_cvt_pk_bf16_f32 v40, v108, v109
	v_cvt_pk_bf16_f32 v41, v110, v111
	v_cvt_pk_bf16_f32 v42, v112, v113
	v_cvt_pk_bf16_f32 v43, v114, v115
	v_mul_f32_e32 v108, v108, v108
	v_mul_f32_e32 v109, v109, v109
	v_mul_f32_e32 v110, v110, v110
	v_mul_f32_e32 v111, v111, v111
	v_mul_f32_e32 v112, v112, v112
	v_mul_f32_e32 v113, v113, v113
	v_mul_f32_e32 v114, v114, v114
	v_mul_f32_e32 v115, v115, v115
	v_add_f32_e32 v108, v108, v109
	v_add_f32_e32 v110, v110, v111
	v_add_f32_e32 v108, v108, v110
	v_add_f32_e32 v112, v112, v113
	v_add_f32_e32 v108, v108, v112
	v_add_f32_e32 v114, v114, v115
	v_add_f32_e32 v108, v108, v114
	v_add_f32_e32 v2, v2, v108
	s_waitcnt lgkmcnt(0)
	v_mfma_f32_16x16x32_bf16 v[6:9], v[40:43], v[22:25], v[6:9]
	s_waitcnt vmcnt(26)
	ds_read_b128 v[14:17], v34 offset:2048
	v_cvt_pk_bf16_f32 v44, v116, v117
	v_cvt_pk_bf16_f32 v45, v118, v119
	v_cvt_pk_bf16_f32 v46, v120, v121
	v_cvt_pk_bf16_f32 v47, v122, v123
	v_mul_f32_e32 v116, v116, v116
	v_mul_f32_e32 v117, v117, v117
	v_mul_f32_e32 v118, v118, v118
	v_mul_f32_e32 v119, v119, v119
	v_mul_f32_e32 v120, v120, v120
	v_mul_f32_e32 v121, v121, v121
	v_mul_f32_e32 v122, v122, v122
	v_mul_f32_e32 v123, v123, v123
	v_add_f32_e32 v116, v116, v117
	v_add_f32_e32 v118, v118, v119
	v_add_f32_e32 v116, v116, v118
	v_add_f32_e32 v120, v120, v121
	v_add_f32_e32 v116, v116, v120
	v_add_f32_e32 v122, v122, v123
	v_add_f32_e32 v116, v116, v122
	v_add_f32_e32 v2, v2, v116
	s_waitcnt lgkmcnt(0)
; __device__ __forceinline__ unsigned cvt_pk_bf16(float lo, float hi) { unsigned r; asm volatile("v_cvt_pk_bf16_f32 %0, %1, %2" : "=v"(r) : "v"(lo), "v"(hi)); return r; }
; __device__ __forceinline__ void x_half(KA a, int grp, int half, int lane, f32x4& acc, float& ss) {
;     ...
;     const int row0 = grp * 16, r = lane & 15, quad = lane >> 4, kbase = half * 1024;
;     const float* xr = x + (size_t)(row0 + r) * D_ + quad * 8 + kbase; bf16_t* br = XB + (size_t)(row0 + r) * D_ + quad * 8 + kbase;
;     const float* wp = W + (size_t)(kbase + quad * 8) * 6160 + 6144 + r; const float* gp = gmix + kbase + quad * 8;
;     acc = (f32x4){0.f, 0.f, 0.f, 0.f}; ss = 0.f;
; #pragma unroll 4
;     for (int k0 = 0; k0 < 1024; k0 += 32) {
;         const f32x4 a0 = *(const f32x4*)(xr + k0), a1 = *(const f32x4*)(xr + k0 + 4);
;         ss += (a0[0] * a0[0] + a0[1] * a0[1]) + (a0[2] * a0[2] + a0[3] * a0[3]) + (a1[0] * a1[0] + a1[1] * a1[1]) + (a1[2] * a1[2] + a1[3] * a1[3]);
;         u32x4 aw; aw.x = cvt_pk_bf16(a0[0], a0[1]); aw.y = cvt_pk_bf16(a0[2], a0[3]); aw.z = cvt_pk_bf16(a1[0], a1[1]); aw.w = cvt_pk_bf16(a1[2], a1[3]);
;         *(u32x4*)(br + k0) = aw;
;         const f32x4 g0 = *(const f32x4*)(gp + k0), g1 = *(const f32x4*)(gp + k0 + 4);
;         const float* w = wp + (size_t)k0 * 6160;
;         u32x4 bw; bw.x = cvt_pk_bf16(w[0] * g0[0], w[6160] * g0[1]); bw.y = cvt_pk_bf16(w[2 * 6160] * g0[2], w[3 * 6160] * g0[3]);
;         bw.z = cvt_pk_bf16(w[4 * 6160] * g1[0], w[5 * 6160] * g1[1]); bw.w = cvt_pk_bf16(w[6 * 6160] * g1[2], w[7 * 6160] * g1[3]);
;         acc = __builtin_amdgcn_mfma_f32_16x16x32_bf16(__builtin_bit_cast(bf16x8, aw), __builtin_bit_cast(bf16x8, bw), acc, 0, 0, 0);
;     }
	v_mfma_f32_16x16x32_bf16 v[6:9], v[44:47], v[14:17], v[6:9]
	s_waitcnt vmcnt(24)
	ds_read_b128 v[22:25], v34 offset:3072
	v_cvt_pk_bf16_f32 v48, v124, v125
	v_cvt_pk_bf16_f32 v49, v126, v127
	v_cvt_pk_bf16_f32 v50, v128, v129
	v_cvt_pk_bf16_f32 v51, v130, v131
	v_mul_f32_e32 v124, v124, v124
	v_mul_f32_e32 v125, v125, v125
	v_mul_f32_e32 v126, v126, v126
	v_mul_f32_e32 v127, v127, v127
	v_mul_f32_e32 v128, v128, v128
	v_mul_f32_e32 v129, v129, v129
	v_mul_f32_e32 v130, v130, v130
	v_mul_f32_e32 v131, v131, v131
	v_add_f32_e32 v124, v124, v125
	v_add_f32_e32 v126, v126, v127
	v_add_f32_e32 v124, v124, v126
	v_add_f32_e32 v128, v128, v129
	v_add_f32_e32 v124, v124, v128
	v_add_f32_e32 v130, v130, v131
	v_add_f32_e32 v124, v124, v130
	v_add_f32_e32 v2, v2, v124
	s_waitcnt lgkmcnt(0)
	v_mfma_f32_16x16x32_bf16 v[6:9], v[48:51], v[22:25], v[6:9]
	s_waitcnt vmcnt(22)
	ds_read_b128 v[14:17], v34 offset:4096
	v_cvt_pk_bf16_f32 v52, v132, v133
	v_cvt_pk_bf16_f32 v53, v134, v135
	v_cvt_pk_bf16_f32 v54, v136, v137
	v_cvt_pk_bf16_f32 v55, v138, v139
	v_mul_f32_e32 v132, v132, v132
	v_mul_f32_e32 v133, v133, v133
	v_mul_f32_e32 v134, v134, v134
	v_mul_f32_e32 v135, v135, v135
	v_mul_f32_e32 v136, v136, v136
	v_mul_f32_e32 v137, v137, v137
	v_mul_f32_e32 v138, v138, v138
	v_mul_f32_e32 v139, v139, v139
	v_add_f32_e32 v132, v132, v133
	v_add_f32_e32 v134, v134, v135
	v_add_f32_e32 v132, v132, v134
	v_add_f32_e32 v136, v136, v137
	v_add_f32_e32 v132, v132, v136
	v_add_f32_e32 v138, v138, v139
	v_add_f32_e32 v132, v132, v138
	v_add_f32_e32 v2, v2, v132
	s_waitcnt lgkmcnt(0)
	v_mfma_f32_16x16x32_bf16 v[6:9], v[52:55], v[14:17], v[6:9]
	s_waitcnt vmcnt(20)
	ds_read_b128 v[22:25], v34 offset:5120
	v_cvt_pk_bf16_f32 v232, v140, v141
	v_cvt_pk_bf16_f32 v233, v142, v143
	v_cvt_pk_bf16_f32 v234, v144, v145
	v_cvt_pk_bf16_f32 v235, v146, v147
	v_mul_f32_e32 v140, v140, v140
	v_mul_f32_e32 v141, v141, v141
	v_mul_f32_e32 v142, v142, v142
	v_mul_f32_e32 v143, v143, v143
	v_mul_f32_e32 v144, v144, v144
	v_mul_f32_e32 v145, v145, v145
	v_mul_f32_e32 v146, v146, v146
	v_mul_f32_e32 v147, v147, v147
	v_add_f32_e32 v140, v140, v141
	v_add_f32_e32 v142, v142, v143
	v_add_f32_e32 v140, v140, v142
	v_add_f32_e32 v144, v144, v145
	v_add_f32_e32 v140, v140, v144
	v_add_f32_e32 v146, v146, v147
	v_add_f32_e32 v140, v140, v146
	v_add_f32_e32 v2, v2, v140
	s_waitcnt lgkmcnt(0)
	v_mfma_f32_16x16x32_bf16 v[6:9], v[232:235], v[22:25], v[6:9]
	s_waitcnt vmcnt(18)
	ds_read_b128 v[14:17], v34 offset:6144
	v_cvt_pk_bf16_f32 v236, v148, v149
	v_cvt_pk_bf16_f32 v237, v150, v151
	v_cvt_pk_bf16_f32 v238, v152, v153
	v_cvt_pk_bf16_f32 v239, v154, v155
	v_mul_f32_e32 v148, v148, v148
	v_mul_f32_e32 v149, v149, v149
	v_mul_f32_e32 v150, v150, v150
	v_mul_f32_e32 v151, v151, v151
	v_mul_f32_e32 v152, v152, v152
	v_mul_f32_e32 v153, v153, v153
	v_mul_f32_e32 v154, v154, v154
	v_mul_f32_e32 v155, v155, v155
	v_add_f32_e32 v148, v148, v149
	v_add_f32_e32 v150, v150, v151
	v_add_f32_e32 v148, v148, v150
	v_add_f32_e32 v152, v152, v153
	v_add_f32_e32 v148, v148, v152
	v_add_f32_e32 v154, v154, v155
	v_add_f32_e32 v148, v148, v154
	v_add_f32_e32 v2, v2, v148
	s_waitcnt lgkmcnt(0)
	v_mfma_f32_16x16x32_bf16 v[6:9], v[236:239], v[14:17], v[6:9]
	s_waitcnt vmcnt(16)
	ds_read_b128 v[22:25], v34 offset:7168
	v_cvt_pk_bf16_f32 v240, v156, v157
	v_cvt_pk_bf16_f32 v241, v158, v159
	v_cvt_pk_bf16_f32 v242, v160, v161
	v_cvt_pk_bf16_f32 v243, v162, v163
	v_mul_f32_e32 v156, v156, v156
	v_mul_f32_e32 v157, v157, v157
	v_mul_f32_e32 v158, v158, v158
	v_mul_f32_e32 v159, v159, v159
	v_mul_f32_e32 v160, v160, v160
	v_mul_f32_e32 v161, v161, v161
	v_mul_f32_e32 v162, v162, v162
	v_mul_f32_e32 v163, v163, v163
	v_add_f32_e32 v156, v156, v157
	v_add_f32_e32 v158, v158, v159
	v_add_f32_e32 v156, v156, v158
	v_add_f32_e32 v160, v160, v161
	v_add_f32_e32 v156, v156, v160
	v_add_f32_e32 v162, v162, v163
	v_add_f32_e32 v156, v156, v162
	v_add_f32_e32 v2, v2, v156
	s_waitcnt lgkmcnt(0)
	v_mfma_f32_16x16x32_bf16 v[6:9], v[240:243], v[22:25], v[6:9]
	global_store_dwordx4 v[70:71], v[36:39], off offset:-128
	global_store_dwordx4 v[70:71], v[40:43], off offset:-64
	global_store_dwordx4 v[70:71], v[44:47], off
	global_store_dwordx4 v[70:71], v[48:51], off offset:64
	global_store_dwordx4 v[70:71], v[52:55], off offset:128
	global_store_dwordx4 v[70:71], v[232:235], off offset:192
	global_store_dwordx4 v[70:71], v[236:239], off offset:256
	global_store_dwordx4 v[70:71], v[240:243], off offset:320
	s_mov_b64 s[30:31], 0x200
	v_lshl_add_u64 v[70:71], v[70:71], 0, s[30:31]
	s_mov_b64 s[30:31], 0x800
	v_lshl_add_u64 v[4:5], v[4:5], 0, s[30:31]
	global_load_dwordx4 v[100:103], v[4:5], off
	global_load_dwordx4 v[104:107], v[4:5], off offset:16
	global_load_dwordx4 v[108:111], v[4:5], off offset:128
	global_load_dwordx4 v[112:115], v[4:5], off offset:144
	global_load_dwordx4 v[116:119], v[4:5], off offset:256
	global_load_dwordx4 v[120:123], v[4:5], off offset:272
	global_load_dwordx4 v[124:127], v[4:5], off offset:384
	global_load_dwordx4 v[128:131], v[4:5], off offset:400
	global_load_dwordx4 v[132:135], v[4:5], off offset:512
	global_load_dwordx4 v[136:139], v[4:5], off offset:528
	global_load_dwordx4 v[140:143], v[4:5], off offset:640
	global_load_dwordx4 v[144:147], v[4:5], off offset:656
	global_load_dwordx4 v[148:151], v[4:5], off offset:768
	global_load_dwordx4 v[152:155], v[4:5], off offset:784
	global_load_dwordx4 v[156:159], v[4:5], off offset:896
	global_load_dwordx4 v[160:163], v[4:5], off offset:912
	s_waitcnt vmcnt(38)
; __device__ __forceinline__ unsigned cvt_pk_bf16(float lo, float hi) { unsigned r; asm volatile("v_cvt_pk_bf16_f32 %0, %1, %2" : "=v"(r) : "v"(lo), "v"(hi)); return r; }
; __device__ __forceinline__ void x_half(KA a, int grp, int half, int lane, f32x4& acc, float& ss) {
;     ...
;     const int row0 = grp * 16, r = lane & 15, quad = lane >> 4, kbase = half * 1024;
;     const float* xr = x + (size_t)(row0 + r) * D_ + quad * 8 + kbase; bf16_t* br = XB + (size_t)(row0 + r) * D_ + quad * 8 + kbase;
;     const float* wp = W + (size_t)(kbase + quad * 8) * 6160 + 6144 + r; const float* gp = gmix + kbase + quad * 8;
;     acc = (f32x4){0.f, 0.f, 0.f, 0.f}; ss = 0.f;
; #pragma unroll 4
;     for (int k0 = 0; k0 < 1024; k0 += 32) {
;         const f32x4 a0 = *(const f32x4*)(xr + k0), a1 = *(const f32x4*)(xr + k0 + 4);
;         ss += (a0[0] * a0[0] + a0[1] * a0[1]) + (a0[2] * a0[2] + a0[3] * a0[3]) + (a1[0] * a1[0] + a1[1] * a1[1]) + (a1[2] * a1[2] + a1[3] * a1[3]);
;         u32x4 aw; aw.x = cvt_pk_bf16(a0[0], a0[1]); aw.y = cvt_pk_bf16(a0[2], a0[3]); aw.z = cvt_pk_bf16(a1[0], a1[1]); aw.w = cvt_pk_bf16(a1[2], a1[3]);
;         *(u32x4*)(br + k0) = aw;
;         const f32x4 g0 = *(const f32x4*)(gp + k0), g1 = *(const f32x4*)(gp + k0 + 4);
;         const float* w = wp + (size_t)k0 * 6160;
;         u32x4 bw; bw.x = cvt_pk_bf16(w[0] * g0[0], w[6160] * g0[1]); bw.y = cvt_pk_bf16(w[2 * 6160] * g0[2], w[3 * 6160] * g0[3]);
;         bw.z = cvt_pk_bf16(w[4 * 6160] * g1[0], w[5 * 6160] * g1[1]); bw.w = cvt_pk_bf16(w[6 * 6160] * g1[2], w[7 * 6160] * g1[3]);
;         acc = __builtin_amdgcn_mfma_f32_16x16x32_bf16(__builtin_bit_cast(bf16x8, aw), __builtin_bit_cast(bf16x8, bw), acc, 0, 0, 0);
;     }
	ds_read_b128 v[14:17], v34 offset:8192
	v_cvt_pk_bf16_f32 v36, v168, v169
	v_cvt_pk_bf16_f32 v37, v170, v171
	v_cvt_pk_bf16_f32 v38, v172, v173
	v_cvt_pk_bf16_f32 v39, v174, v175
	v_mul_f32_e32 v168, v168, v168
	v_mul_f32_e32 v169, v169, v169
	v_mul_f32_e32 v170, v170, v170
	v_mul_f32_e32 v171, v171, v171
	v_mul_f32_e32 v172, v172, v172
	v_mul_f32_e32 v173, v173, v173
	v_mul_f32_e32 v174, v174, v174
	v_mul_f32_e32 v175, v175, v175
	v_add_f32_e32 v168, v168, v169
	v_add_f32_e32 v170, v170, v171
	v_add_f32_e32 v168, v168, v170
	v_add_f32_e32 v172, v172, v173
	v_add_f32_e32 v168, v168, v172
	v_add_f32_e32 v174, v174, v175
	v_add_f32_e32 v168, v168, v174
	v_add_f32_e32 v2, v2, v168
	s_waitcnt lgkmcnt(0)
	v_mfma_f32_16x16x32_bf16 v[6:9], v[36:39], v[14:17], v[6:9]
	s_waitcnt vmcnt(36)
	ds_read_b128 v[22:25], v34 offset:9216
	v_cvt_pk_bf16_f32 v40, v176, v177
	v_cvt_pk_bf16_f32 v41, v178, v179
	v_cvt_pk_bf16_f32 v42, v180, v181
	v_cvt_pk_bf16_f32 v43, v182, v183
	v_mul_f32_e32 v176, v176, v176
	v_mul_f32_e32 v177, v177, v177
	v_mul_f32_e32 v178, v178, v178
	v_mul_f32_e32 v179, v179, v179
	v_mul_f32_e32 v180, v180, v180
	v_mul_f32_e32 v181, v181, v181
	v_mul_f32_e32 v182, v182, v182
	v_mul_f32_e32 v183, v183, v183
	v_add_f32_e32 v176, v176, v177
	v_add_f32_e32 v178, v178, v179
	v_add_f32_e32 v176, v176, v178
	v_add_f32_e32 v180, v180, v181
	v_add_f32_e32 v176, v176, v180
	v_add_f32_e32 v182, v182, v183
	v_add_f32_e32 v176, v176, v182
	v_add_f32_e32 v2, v2, v176
	s_waitcnt lgkmcnt(0)
	v_mfma_f32_16x16x32_bf16 v[6:9], v[40:43], v[22:25], v[6:9]
	s_waitcnt vmcnt(34)
	ds_read_b128 v[14:17], v34 offset:10240
	v_cvt_pk_bf16_f32 v44, v184, v185
	v_cvt_pk_bf16_f32 v45, v186, v187
	v_cvt_pk_bf16_f32 v46, v188, v189
	v_cvt_pk_bf16_f32 v47, v190, v191
	v_mul_f32_e32 v184, v184, v184
	v_mul_f32_e32 v185, v185, v185
	v_mul_f32_e32 v186, v186, v186
	v_mul_f32_e32 v187, v187, v187
	v_mul_f32_e32 v188, v188, v188
	v_mul_f32_e32 v189, v189, v189
	v_mul_f32_e32 v190, v190, v190
	v_mul_f32_e32 v191, v191, v191
	v_add_f32_e32 v184, v184, v185
	v_add_f32_e32 v186, v186, v187
	v_add_f32_e32 v184, v184, v186
	v_add_f32_e32 v188, v188, v189
	v_add_f32_e32 v184, v184, v188
	v_add_f32_e32 v190, v190, v191
	v_add_f32_e32 v184, v184, v190
	v_add_f32_e32 v2, v2, v184
	s_waitcnt lgkmcnt(0)
	v_mfma_f32_16x16x32_bf16 v[6:9], v[44:47], v[14:17], v[6:9]
	s_waitcnt vmcnt(32)
	ds_read_b128 v[22:25], v34 offset:11264
	v_cvt_pk_bf16_f32 v48, v192, v193
	v_cvt_pk_bf16_f32 v49, v194, v195
	v_cvt_pk_bf16_f32 v50, v196, v197
	v_cvt_pk_bf16_f32 v51, v198, v199
	v_mul_f32_e32 v192, v192, v192
	v_mul_f32_e32 v193, v193, v193
	v_mul_f32_e32 v194, v194, v194
	v_mul_f32_e32 v195, v195, v195
	v_mul_f32_e32 v196, v196, v196
	v_mul_f32_e32 v197, v197, v197
	v_mul_f32_e32 v198, v198, v198
	v_mul_f32_e32 v199, v199, v199
	v_add_f32_e32 v192, v192, v193
	v_add_f32_e32 v194, v194, v195
	v_add_f32_e32 v192, v192, v194
	v_add_f32_e32 v196, v196, v197
	v_add_f32_e32 v192, v192, v196
	v_add_f32_e32 v198, v198, v199
	v_add_f32_e32 v192, v192, v198
	v_add_f32_e32 v2, v2, v192
	s_waitcnt lgkmcnt(0)
	v_mfma_f32_16x16x32_bf16 v[6:9], v[48:51], v[22:25], v[6:9]
	s_waitcnt vmcnt(30)
	ds_read_b128 v[14:17], v34 offset:12288
	v_cvt_pk_bf16_f32 v52, v200, v201
	v_cvt_pk_bf16_f32 v53, v202, v203
	v_cvt_pk_bf16_f32 v54, v204, v205
	v_cvt_pk_bf16_f32 v55, v206, v207
	v_mul_f32_e32 v200, v200, v200
	v_mul_f32_e32 v201, v201, v201
	v_mul_f32_e32 v202, v202, v202
	v_mul_f32_e32 v203, v203, v203
	v_mul_f32_e32 v204, v204, v204
	v_mul_f32_e32 v205, v205, v205
	v_mul_f32_e32 v206, v206, v206
	v_mul_f32_e32 v207, v207, v207
	v_add_f32_e32 v200, v200, v201
	v_add_f32_e32 v202, v202, v203
	v_add_f32_e32 v200, v200, v202
	v_add_f32_e32 v204, v204, v205
	v_add_f32_e32 v200, v200, v204
	v_add_f32_e32 v206, v206, v207
	v_add_f32_e32 v200, v200, v206
	v_add_f32_e32 v2, v2, v200
	s_waitcnt lgkmcnt(0)
	v_mfma_f32_16x16x32_bf16 v[6:9], v[52:55], v[14:17], v[6:9]
	s_waitcnt vmcnt(28)
	ds_read_b128 v[22:25], v34 offset:13312
	v_cvt_pk_bf16_f32 v232, v208, v209
	v_cvt_pk_bf16_f32 v233, v210, v211
	v_cvt_pk_bf16_f32 v234, v212, v213
	v_cvt_pk_bf16_f32 v235, v214, v215
	v_mul_f32_e32 v208, v208, v208
	v_mul_f32_e32 v209, v209, v209
	v_mul_f32_e32 v210, v210, v210
	v_mul_f32_e32 v211, v211, v211
	v_mul_f32_e32 v212, v212, v212
	v_mul_f32_e32 v213, v213, v213
	v_mul_f32_e32 v214, v214, v214
	v_mul_f32_e32 v215, v215, v215
	v_add_f32_e32 v208, v208, v209
	v_add_f32_e32 v210, v210, v211
	v_add_f32_e32 v208, v208, v210
	v_add_f32_e32 v212, v212, v213
	v_add_f32_e32 v208, v208, v212
	v_add_f32_e32 v214, v214, v215
	v_add_f32_e32 v208, v208, v214
	v_add_f32_e32 v2, v2, v208
	s_waitcnt lgkmcnt(0)
	v_mfma_f32_16x16x32_bf16 v[6:9], v[232:235], v[22:25], v[6:9]
	s_waitcnt vmcnt(26)
	ds_read_b128 v[14:17], v34 offset:14336
	v_cvt_pk_bf16_f32 v236, v216, v217
	v_cvt_pk_bf16_f32 v237, v218, v219
	v_cvt_pk_bf16_f32 v238, v220, v221
	v_cvt_pk_bf16_f32 v239, v222, v223
	v_mul_f32_e32 v216, v216, v216
	v_mul_f32_e32 v217, v217, v217
	v_mul_f32_e32 v218, v218, v218
	v_mul_f32_e32 v219, v219, v219
	v_mul_f32_e32 v220, v220, v220
	v_mul_f32_e32 v221, v221, v221
	v_mul_f32_e32 v222, v222, v222
	v_mul_f32_e32 v223, v223, v223
	v_add_f32_e32 v216, v216, v217
	v_add_f32_e32 v218, v218, v219
	v_add_f32_e32 v216, v216, v218
	v_add_f32_e32 v220, v220, v221
	v_add_f32_e32 v216, v216, v220
	v_add_f32_e32 v222, v222, v223
	v_add_f32_e32 v216, v216, v222
	v_add_f32_e32 v2, v2, v216
	s_waitcnt lgkmcnt(0)
	v_mfma_f32_16x16x32_bf16 v[6:9], v[236:239], v[14:17], v[6:9]
	s_waitcnt vmcnt(24)
; __device__ __forceinline__ unsigned cvt_pk_bf16(float lo, float hi) { unsigned r; asm volatile("v_cvt_pk_bf16_f32 %0, %1, %2" : "=v"(r) : "v"(lo), "v"(hi)); return r; }
; __device__ __forceinline__ void x_half(KA a, int grp, int half, int lane, f32x4& acc, float& ss) {
;     ...
;     const int row0 = grp * 16, r = lane & 15, quad = lane >> 4, kbase = half * 1024;
;     const float* xr = x + (size_t)(row0 + r) * D_ + quad * 8 + kbase; bf16_t* br = XB + (size_t)(row0 + r) * D_ + quad * 8 + kbase;
;     const float* wp = W + (size_t)(kbase + quad * 8) * 6160 + 6144 + r; const float* gp = gmix + kbase + quad * 8;
;     acc = (f32x4){0.f, 0.f, 0.f, 0.f}; ss = 0.f;
; #pragma unroll 4
;     for (int k0 = 0; k0 < 1024; k0 += 32) {
;         const f32x4 a0 = *(const f32x4*)(xr + k0), a1 = *(const f32x4*)(xr + k0 + 4);
;         ss += (a0[0] * a0[0] + a0[1] * a0[1]) + (a0[2] * a0[2] + a0[3] * a0[3]) + (a1[0] * a1[0] + a1[1] * a1[1]) + (a1[2] * a1[2] + a1[3] * a1[3]);
;         u32x4 aw; aw.x = cvt_pk_bf16(a0[0], a0[1]); aw.y = cvt_pk_bf16(a0[2], a0[3]); aw.z = cvt_pk_bf16(a1[0], a1[1]); aw.w = cvt_pk_bf16(a1[2], a1[3]);
;         *(u32x4*)(br + k0) = aw;
;         const f32x4 g0 = *(const f32x4*)(gp + k0), g1 = *(const f32x4*)(gp + k0 + 4);
;         const float* w = wp + (size_t)k0 * 6160;
;         u32x4 bw; bw.x = cvt_pk_bf16(w[0] * g0[0], w[6160] * g0[1]); bw.y = cvt_pk_bf16(w[2 * 6160] * g0[2], w[3 * 6160] * g0[3]);
;         bw.z = cvt_pk_bf16(w[4 * 6160] * g1[0], w[5 * 6160] * g1[1]); bw.w = cvt_pk_bf16(w[6 * 6160] * g1[2], w[7 * 6160] * g1[3]);
;         acc = __builtin_amdgcn_mfma_f32_16x16x32_bf16(__builtin_bit_cast(bf16x8, aw), __builtin_bit_cast(bf16x8, bw), acc, 0, 0, 0);
;     }
	ds_read_b128 v[22:25], v34 offset:15360
	v_cvt_pk_bf16_f32 v240, v224, v225
	v_cvt_pk_bf16_f32 v241, v226, v227
	v_cvt_pk_bf16_f32 v242, v228, v229
	v_cvt_pk_bf16_f32 v243, v230, v231
	v_mul_f32_e32 v224, v224, v224
	v_mul_f32_e32 v225, v225, v225
	v_mul_f32_e32 v226, v226, v226
	v_mul_f32_e32 v227, v227, v227
	v_mul_f32_e32 v228, v228, v228
	v_mul_f32_e32 v229, v229, v229
	v_mul_f32_e32 v230, v230, v230
	v_mul_f32_e32 v231, v231, v231
	v_add_f32_e32 v224, v224, v225
	v_add_f32_e32 v226, v226, v227
	v_add_f32_e32 v224, v224, v226
	v_add_f32_e32 v228, v228, v229
	v_add_f32_e32 v224, v224, v228
	v_add_f32_e32 v230, v230, v231
	v_add_f32_e32 v224, v224, v230
	v_add_f32_e32 v2, v2, v224
	s_waitcnt lgkmcnt(0)
	v_mfma_f32_16x16x32_bf16 v[6:9], v[240:243], v[22:25], v[6:9]
	global_store_dwordx4 v[70:71], v[36:39], off offset:-128
	global_store_dwordx4 v[70:71], v[40:43], off offset:-64
	global_store_dwordx4 v[70:71], v[44:47], off
	global_store_dwordx4 v[70:71], v[48:51], off offset:64
	global_store_dwordx4 v[70:71], v[52:55], off offset:128
	global_store_dwordx4 v[70:71], v[232:235], off offset:192
	global_store_dwordx4 v[70:71], v[236:239], off offset:256
	global_store_dwordx4 v[70:71], v[240:243], off offset:320
	s_mov_b64 s[30:31], 0x200
	v_lshl_add_u64 v[70:71], v[70:71], 0, s[30:31]
	s_mov_b64 s[30:31], 0x400
	v_lshl_add_u64 v[4:5], v[4:5], 0, s[30:31]
	global_load_dwordx4 v[168:171], v[4:5], off
	global_load_dwordx4 v[172:175], v[4:5], off offset:16
	global_load_dwordx4 v[176:179], v[4:5], off offset:128
	global_load_dwordx4 v[180:183], v[4:5], off offset:144
	global_load_dwordx4 v[184:187], v[4:5], off offset:256
	global_load_dwordx4 v[188:191], v[4:5], off offset:272
	global_load_dwordx4 v[192:195], v[4:5], off offset:384
	global_load_dwordx4 v[196:199], v[4:5], off offset:400
	global_load_dwordx4 v[200:203], v[4:5], off offset:512
	global_load_dwordx4 v[204:207], v[4:5], off offset:528
	global_load_dwordx4 v[208:211], v[4:5], off offset:640
	global_load_dwordx4 v[212:215], v[4:5], off offset:656
	global_load_dwordx4 v[216:219], v[4:5], off offset:768
	global_load_dwordx4 v[220:223], v[4:5], off offset:784
	global_load_dwordx4 v[224:227], v[4:5], off offset:896
	global_load_dwordx4 v[228:231], v[4:5], off offset:912
	s_waitcnt vmcnt(38)
	ds_read_b128 v[14:17], v34 offset:16384
	v_cvt_pk_bf16_f32 v36, v100, v101
	v_cvt_pk_bf16_f32 v37, v102, v103
	v_cvt_pk_bf16_f32 v38, v104, v105
	v_cvt_pk_bf16_f32 v39, v106, v107
	v_mul_f32_e32 v100, v100, v100
	v_mul_f32_e32 v101, v101, v101
	v_mul_f32_e32 v102, v102, v102
	v_mul_f32_e32 v103, v103, v103
	v_mul_f32_e32 v104, v104, v104
	v_mul_f32_e32 v105, v105, v105
	v_mul_f32_e32 v106, v106, v106
	v_mul_f32_e32 v107, v107, v107
	v_add_f32_e32 v100, v100, v101
	v_add_f32_e32 v102, v102, v103
	v_add_f32_e32 v100, v100, v102
	v_add_f32_e32 v104, v104, v105
	v_add_f32_e32 v100, v100, v104
	v_add_f32_e32 v106, v106, v107
	v_add_f32_e32 v100, v100, v106
	v_add_f32_e32 v2, v2, v100
	s_waitcnt lgkmcnt(0)
	v_mfma_f32_16x16x32_bf16 v[6:9], v[36:39], v[14:17], v[6:9]
	s_waitcnt vmcnt(36)
	ds_read_b128 v[22:25], v34 offset:17408
	v_cvt_pk_bf16_f32 v40, v108, v109
	v_cvt_pk_bf16_f32 v41, v110, v111
	v_cvt_pk_bf16_f32 v42, v112, v113
	v_cvt_pk_bf16_f32 v43, v114, v115
	v_mul_f32_e32 v108, v108, v108
	v_mul_f32_e32 v109, v109, v109
	v_mul_f32_e32 v110, v110, v110
	v_mul_f32_e32 v111, v111, v111
	v_mul_f32_e32 v112, v112, v112
	v_mul_f32_e32 v113, v113, v113
	v_mul_f32_e32 v114, v114, v114
	v_mul_f32_e32 v115, v115, v115
	v_add_f32_e32 v108, v108, v109
	v_add_f32_e32 v110, v110, v111
	v_add_f32_e32 v108, v108, v110
	v_add_f32_e32 v112, v112, v113
	v_add_f32_e32 v108, v108, v112
	v_add_f32_e32 v114, v114, v115
	v_add_f32_e32 v108, v108, v114
	v_add_f32_e32 v2, v2, v108
	s_waitcnt lgkmcnt(0)
	v_mfma_f32_16x16x32_bf16 v[6:9], v[40:43], v[22:25], v[6:9]
	s_waitcnt vmcnt(34)
	ds_read_b128 v[14:17], v34 offset:18432
	v_cvt_pk_bf16_f32 v44, v116, v117
	v_cvt_pk_bf16_f32 v45, v118, v119
	v_cvt_pk_bf16_f32 v46, v120, v121
	v_cvt_pk_bf16_f32 v47, v122, v123
	v_mul_f32_e32 v116, v116, v116
	v_mul_f32_e32 v117, v117, v117
	v_mul_f32_e32 v118, v118, v118
	v_mul_f32_e32 v119, v119, v119
	v_mul_f32_e32 v120, v120, v120
	v_mul_f32_e32 v121, v121, v121
	v_mul_f32_e32 v122, v122, v122
	v_mul_f32_e32 v123, v123, v123
	v_add_f32_e32 v116, v116, v117
	v_add_f32_e32 v118, v118, v119
	v_add_f32_e32 v116, v116, v118
	v_add_f32_e32 v120, v120, v121
	v_add_f32_e32 v116, v116, v120
	v_add_f32_e32 v122, v122, v123
	v_add_f32_e32 v116, v116, v122
	v_add_f32_e32 v2, v2, v116
	s_waitcnt lgkmcnt(0)
	v_mfma_f32_16x16x32_bf16 v[6:9], v[44:47], v[14:17], v[6:9]
	s_waitcnt vmcnt(32)
	ds_read_b128 v[22:25], v34 offset:19456
	v_cvt_pk_bf16_f32 v48, v124, v125
	v_cvt_pk_bf16_f32 v49, v126, v127
	v_cvt_pk_bf16_f32 v50, v128, v129
	v_cvt_pk_bf16_f32 v51, v130, v131
	v_mul_f32_e32 v124, v124, v124
	v_mul_f32_e32 v125, v125, v125
	v_mul_f32_e32 v126, v126, v126
	v_mul_f32_e32 v127, v127, v127
	v_mul_f32_e32 v128, v128, v128
	v_mul_f32_e32 v129, v129, v129
	v_mul_f32_e32 v130, v130, v130
	v_mul_f32_e32 v131, v131, v131
	v_add_f32_e32 v124, v124, v125
	v_add_f32_e32 v126, v126, v127
	v_add_f32_e32 v124, v124, v126
	v_add_f32_e32 v128, v128, v129
	v_add_f32_e32 v124, v124, v128
	v_add_f32_e32 v130, v130, v131
	v_add_f32_e32 v124, v124, v130
	v_add_f32_e32 v2, v2, v124
	s_waitcnt lgkmcnt(0)
	v_mfma_f32_16x16x32_bf16 v[6:9], v[48:51], v[22:25], v[6:9]
	s_waitcnt vmcnt(30)
; __device__ __forceinline__ unsigned cvt_pk_bf16(float lo, float hi) { unsigned r; asm volatile("v_cvt_pk_bf16_f32 %0, %1, %2" : "=v"(r) : "v"(lo), "v"(hi)); return r; }
; __device__ __forceinline__ void x_half(KA a, int grp, int half, int lane, f32x4& acc, float& ss) {
;     ...
;     for (int k0 = 0; k0 < 1024; k0 += 32) {
;         const f32x4 a0 = *(const f32x4*)(xr + k0), a1 = *(const f32x4*)(xr + k0 + 4);
;         ss += (a0[0] * a0[0] + a0[1] * a0[1]) + (a0[2] * a0[2] + a0[3] * a0[3]) + (a1[0] * a1[0] + a1[1] * a1[1]) + (a1[2] * a1[2] + a1[3] * a1[3]);
;         u32x4 aw; aw.x = cvt_pk_bf16(a0[0], a0[1]); aw.y = cvt_pk_bf16(a0[2], a0[3]); aw.z = cvt_pk_bf16(a1[0], a1[1]); aw.w = cvt_pk_bf16(a1[2], a1[3]);
;         *(u32x4*)(br + k0) = aw;
;         const f32x4 g0 = *(const f32x4*)(gp + k0), g1 = *(const f32x4*)(gp + k0 + 4);
;         const float* w = wp + (size_t)k0 * 6160;
;         u32x4 bw; bw.x = cvt_pk_bf16(w[0] * g0[0], w[6160] * g0[1]); bw.y = cvt_pk_bf16(w[2 * 6160] * g0[2], w[3 * 6160] * g0[3]);
;         bw.z = cvt_pk_bf16(w[4 * 6160] * g1[0], w[5 * 6160] * g1[1]); bw.w = cvt_pk_bf16(w[6 * 6160] * g1[2], w[7 * 6160] * g1[3]);
;         acc = __builtin_amdgcn_mfma_f32_16x16x32_bf16(__builtin_bit_cast(bf16x8, aw), __builtin_bit_cast(bf16x8, bw), acc, 0, 0, 0);
;     }
	ds_read_b128 v[14:17], v34 offset:20480
	v_cvt_pk_bf16_f32 v52, v132, v133
	v_cvt_pk_bf16_f32 v53, v134, v135
	v_cvt_pk_bf16_f32 v54, v136, v137
	v_cvt_pk_bf16_f32 v55, v138, v139
	v_mul_f32_e32 v132, v132, v132
	v_mul_f32_e32 v133, v133, v133
	v_mul_f32_e32 v134, v134, v134
	v_mul_f32_e32 v135, v135, v135
	v_mul_f32_e32 v136, v136, v136
	v_mul_f32_e32 v137, v137, v137
	v_mul_f32_e32 v138, v138, v138
	v_mul_f32_e32 v139, v139, v139
	v_add_f32_e32 v132, v132, v133
	v_add_f32_e32 v134, v134, v135
	v_add_f32_e32 v132, v132, v134
	v_add_f32_e32 v136, v136, v137
	v_add_f32_e32 v132, v132, v136
	v_add_f32_e32 v138, v138, v139
	v_add_f32_e32 v132, v132, v138
	v_add_f32_e32 v2, v2, v132
	s_waitcnt lgkmcnt(0)
	v_mfma_f32_16x16x32_bf16 v[6:9], v[52:55], v[14:17], v[6:9]
	s_waitcnt vmcnt(28)
	ds_read_b128 v[22:25], v34 offset:21504
	v_cvt_pk_bf16_f32 v232, v140, v141
	v_cvt_pk_bf16_f32 v233, v142, v143
	v_cvt_pk_bf16_f32 v234, v144, v145
	v_cvt_pk_bf16_f32 v235, v146, v147
	v_mul_f32_e32 v140, v140, v140
	v_mul_f32_e32 v141, v141, v141
	v_mul_f32_e32 v142, v142, v142
	v_mul_f32_e32 v143, v143, v143
	v_mul_f32_e32 v144, v144, v144
	v_mul_f32_e32 v145, v145, v145
	v_mul_f32_e32 v146, v146, v146
	v_mul_f32_e32 v147, v147, v147
	v_add_f32_e32 v140, v140, v141
	v_add_f32_e32 v142, v142, v143
	v_add_f32_e32 v140, v140, v142
	v_add_f32_e32 v144, v144, v145
	v_add_f32_e32 v140, v140, v144
	v_add_f32_e32 v146, v146, v147
	v_add_f32_e32 v140, v140, v146
	v_add_f32_e32 v2, v2, v140
	s_waitcnt lgkmcnt(0)
	v_mfma_f32_16x16x32_bf16 v[6:9], v[232:235], v[22:25], v[6:9]
	s_waitcnt vmcnt(26)
	ds_read_b128 v[14:17], v34 offset:22528
	v_cvt_pk_bf16_f32 v236, v148, v149
	v_cvt_pk_bf16_f32 v237, v150, v151
	v_cvt_pk_bf16_f32 v238, v152, v153
	v_cvt_pk_bf16_f32 v239, v154, v155
	v_mul_f32_e32 v148, v148, v148
	v_mul_f32_e32 v149, v149, v149
	v_mul_f32_e32 v150, v150, v150
	v_mul_f32_e32 v151, v151, v151
	v_mul_f32_e32 v152, v152, v152
	v_mul_f32_e32 v153, v153, v153
	v_mul_f32_e32 v154, v154, v154
	v_mul_f32_e32 v155, v155, v155
	v_add_f32_e32 v148, v148, v149
	v_add_f32_e32 v150, v150, v151
	v_add_f32_e32 v148, v148, v150
	v_add_f32_e32 v152, v152, v153
	v_add_f32_e32 v148, v148, v152
	v_add_f32_e32 v154, v154, v155
	v_add_f32_e32 v148, v148, v154
	v_add_f32_e32 v2, v2, v148
	s_waitcnt lgkmcnt(0)
	v_mfma_f32_16x16x32_bf16 v[6:9], v[236:239], v[14:17], v[6:9]
	s_waitcnt vmcnt(24)
	ds_read_b128 v[22:25], v34 offset:23552
	v_cvt_pk_bf16_f32 v240, v156, v157
	v_cvt_pk_bf16_f32 v241, v158, v159
	v_cvt_pk_bf16_f32 v242, v160, v161
	v_cvt_pk_bf16_f32 v243, v162, v163
	v_mul_f32_e32 v156, v156, v156
	v_mul_f32_e32 v157, v157, v157
	v_mul_f32_e32 v158, v158, v158
	v_mul_f32_e32 v159, v159, v159
	v_mul_f32_e32 v160, v160, v160
	v_mul_f32_e32 v161, v161, v161
	v_mul_f32_e32 v162, v162, v162
	v_mul_f32_e32 v163, v163, v163
	v_add_f32_e32 v156, v156, v157
	v_add_f32_e32 v158, v158, v159
	v_add_f32_e32 v156, v156, v158
	v_add_f32_e32 v160, v160, v161
	v_add_f32_e32 v156, v156, v160
	v_add_f32_e32 v162, v162, v163
	v_add_f32_e32 v156, v156, v162
	v_add_f32_e32 v2, v2, v156
	s_waitcnt lgkmcnt(0)
	v_mfma_f32_16x16x32_bf16 v[6:9], v[240:243], v[22:25], v[6:9]
	global_store_dwordx4 v[70:71], v[36:39], off offset:-128
	global_store_dwordx4 v[70:71], v[40:43], off offset:-64
	global_store_dwordx4 v[70:71], v[44:47], off
	global_store_dwordx4 v[70:71], v[48:51], off offset:64
	global_store_dwordx4 v[70:71], v[52:55], off offset:128
	global_store_dwordx4 v[70:71], v[232:235], off offset:192
	global_store_dwordx4 v[70:71], v[236:239], off offset:256
	global_store_dwordx4 v[70:71], v[240:243], off offset:320
	s_mov_b64 s[30:31], 0x200
	v_lshl_add_u64 v[70:71], v[70:71], 0, s[30:31]
	s_waitcnt vmcnt(22)
	ds_read_b128 v[14:17], v34 offset:24576
	v_cvt_pk_bf16_f32 v36, v168, v169
	v_cvt_pk_bf16_f32 v37, v170, v171
	v_cvt_pk_bf16_f32 v38, v172, v173
	v_cvt_pk_bf16_f32 v39, v174, v175
	v_mul_f32_e32 v168, v168, v168
	v_mul_f32_e32 v169, v169, v169
	v_mul_f32_e32 v170, v170, v170
	v_mul_f32_e32 v171, v171, v171
	v_mul_f32_e32 v172, v172, v172
	v_mul_f32_e32 v173, v173, v173
	v_mul_f32_e32 v174, v174, v174
	v_mul_f32_e32 v175, v175, v175
	v_add_f32_e32 v168, v168, v169
	v_add_f32_e32 v170, v170, v171
	v_add_f32_e32 v168, v168, v170
	v_add_f32_e32 v172, v172, v173
	v_add_f32_e32 v168, v168, v172
	v_add_f32_e32 v174, v174, v175
	v_add_f32_e32 v168, v168, v174
	v_add_f32_e32 v2, v2, v168
	s_waitcnt lgkmcnt(0)
	v_mfma_f32_16x16x32_bf16 v[6:9], v[36:39], v[14:17], v[6:9]
	s_waitcnt vmcnt(20)
	ds_read_b128 v[22:25], v34 offset:25600
	v_cvt_pk_bf16_f32 v40, v176, v177
	v_cvt_pk_bf16_f32 v41, v178, v179
	v_cvt_pk_bf16_f32 v42, v180, v181
	v_cvt_pk_bf16_f32 v43, v182, v183
	v_mul_f32_e32 v176, v176, v176
	v_mul_f32_e32 v177, v177, v177
	v_mul_f32_e32 v178, v178, v178
	v_mul_f32_e32 v179, v179, v179
	v_mul_f32_e32 v180, v180, v180
	v_mul_f32_e32 v181, v181, v181
	v_mul_f32_e32 v182, v182, v182
	v_mul_f32_e32 v183, v183, v183
	v_add_f32_e32 v176, v176, v177
	v_add_f32_e32 v178, v178, v179
	v_add_f32_e32 v176, v176, v178
	v_add_f32_e32 v180, v180, v181
	v_add_f32_e32 v176, v176, v180
	v_add_f32_e32 v182, v182, v183
	v_add_f32_e32 v176, v176, v182
	v_add_f32_e32 v2, v2, v176
	s_waitcnt lgkmcnt(0)
	v_mfma_f32_16x16x32_bf16 v[6:9], v[40:43], v[22:25], v[6:9]
	s_waitcnt vmcnt(18)
; __device__ __forceinline__ unsigned cvt_pk_bf16(float lo, float hi) { unsigned r; asm volatile("v_cvt_pk_bf16_f32 %0, %1, %2" : "=v"(r) : "v"(lo), "v"(hi)); return r; }
; #define LAS __attribute__((address_space(3)))
; __device__ __forceinline__ void x_half(KA a, int grp, int half, int lane, f32x4& acc, float& ss) {
;     ...
;     for (int k0 = 0; k0 < 1024; k0 += 32) {
;         const f32x4 a0 = *(const f32x4*)(xr + k0), a1 = *(const f32x4*)(xr + k0 + 4);
;         ss += (a0[0] * a0[0] + a0[1] * a0[1]) + (a0[2] * a0[2] + a0[3] * a0[3]) + (a1[0] * a1[0] + a1[1] * a1[1]) + (a1[2] * a1[2] + a1[3] * a1[3]);
;         u32x4 aw; aw.x = cvt_pk_bf16(a0[0], a0[1]); aw.y = cvt_pk_bf16(a0[2], a0[3]); aw.z = cvt_pk_bf16(a1[0], a1[1]); aw.w = cvt_pk_bf16(a1[2], a1[3]);
;         *(u32x4*)(br + k0) = aw;
;         const f32x4 g0 = *(const f32x4*)(gp + k0), g1 = *(const f32x4*)(gp + k0 + 4);
;         const float* w = wp + (size_t)k0 * 6160;
;         u32x4 bw; bw.x = cvt_pk_bf16(w[0] * g0[0], w[6160] * g0[1]); bw.y = cvt_pk_bf16(w[2 * 6160] * g0[2], w[3 * 6160] * g0[3]);
;         bw.z = cvt_pk_bf16(w[4 * 6160] * g1[0], w[5 * 6160] * g1[1]); bw.w = cvt_pk_bf16(w[6 * 6160] * g1[2], w[7 * 6160] * g1[3]);
;         acc = __builtin_amdgcn_mfma_f32_16x16x32_bf16(__builtin_bit_cast(bf16x8, aw), __builtin_bit_cast(bf16x8, bw), acc, 0, 0, 0);
;     }
; __device__ __forceinline__ void prologue(KA a, LAS unsigned char* lds, int bid, int G, int lane, int wave) {
;     ...
;         LAS float* xs = (LAS float*)(lds + (wave & 3) * 16384 + 12288) + lane * 5;
;         if (wave >= 4) { xs[0] = acc[0]; xs[1] = acc[1]; xs[2] = acc[2]; xs[3] = acc[3]; xs[4] = ss; }
	ds_read_b128 v[14:17], v34 offset:26624
	v_cvt_pk_bf16_f32 v44, v184, v185
	v_cvt_pk_bf16_f32 v45, v186, v187
	v_cvt_pk_bf16_f32 v46, v188, v189
	v_cvt_pk_bf16_f32 v47, v190, v191
	v_mul_f32_e32 v184, v184, v184
	v_mul_f32_e32 v185, v185, v185
	v_mul_f32_e32 v186, v186, v186
	v_mul_f32_e32 v187, v187, v187
	v_mul_f32_e32 v188, v188, v188
	v_mul_f32_e32 v189, v189, v189
	v_mul_f32_e32 v190, v190, v190
	v_mul_f32_e32 v191, v191, v191
	v_add_f32_e32 v184, v184, v185
	v_add_f32_e32 v186, v186, v187
	v_add_f32_e32 v184, v184, v186
	v_add_f32_e32 v188, v188, v189
	v_add_f32_e32 v184, v184, v188
	v_add_f32_e32 v190, v190, v191
	v_add_f32_e32 v184, v184, v190
	v_add_f32_e32 v2, v2, v184
	s_waitcnt lgkmcnt(0)
	v_mfma_f32_16x16x32_bf16 v[6:9], v[44:47], v[14:17], v[6:9]
	s_waitcnt vmcnt(16)
	ds_read_b128 v[22:25], v34 offset:27648
	v_cvt_pk_bf16_f32 v48, v192, v193
	v_cvt_pk_bf16_f32 v49, v194, v195
	v_cvt_pk_bf16_f32 v50, v196, v197
	v_cvt_pk_bf16_f32 v51, v198, v199
	v_mul_f32_e32 v192, v192, v192
	v_mul_f32_e32 v193, v193, v193
	v_mul_f32_e32 v194, v194, v194
	v_mul_f32_e32 v195, v195, v195
	v_mul_f32_e32 v196, v196, v196
	v_mul_f32_e32 v197, v197, v197
	v_mul_f32_e32 v198, v198, v198
	v_mul_f32_e32 v199, v199, v199
	v_add_f32_e32 v192, v192, v193
	v_add_f32_e32 v194, v194, v195
	v_add_f32_e32 v192, v192, v194
	v_add_f32_e32 v196, v196, v197
	v_add_f32_e32 v192, v192, v196
	v_add_f32_e32 v198, v198, v199
	v_add_f32_e32 v192, v192, v198
	v_add_f32_e32 v2, v2, v192
	s_waitcnt lgkmcnt(0)
	v_mfma_f32_16x16x32_bf16 v[6:9], v[48:51], v[22:25], v[6:9]
	s_waitcnt vmcnt(14)
	ds_read_b128 v[14:17], v34 offset:28672
	v_cvt_pk_bf16_f32 v52, v200, v201
	v_cvt_pk_bf16_f32 v53, v202, v203
	v_cvt_pk_bf16_f32 v54, v204, v205
	v_cvt_pk_bf16_f32 v55, v206, v207
	v_mul_f32_e32 v200, v200, v200
	v_mul_f32_e32 v201, v201, v201
	v_mul_f32_e32 v202, v202, v202
	v_mul_f32_e32 v203, v203, v203
	v_mul_f32_e32 v204, v204, v204
	v_mul_f32_e32 v205, v205, v205
	v_mul_f32_e32 v206, v206, v206
	v_mul_f32_e32 v207, v207, v207
	v_add_f32_e32 v200, v200, v201
	v_add_f32_e32 v202, v202, v203
	v_add_f32_e32 v200, v200, v202
	v_add_f32_e32 v204, v204, v205
	v_add_f32_e32 v200, v200, v204
	v_add_f32_e32 v206, v206, v207
	v_add_f32_e32 v200, v200, v206
	v_add_f32_e32 v2, v2, v200
	s_waitcnt lgkmcnt(0)
	v_mfma_f32_16x16x32_bf16 v[6:9], v[52:55], v[14:17], v[6:9]
	s_waitcnt vmcnt(12)
	ds_read_b128 v[22:25], v34 offset:29696
	v_cvt_pk_bf16_f32 v232, v208, v209
	v_cvt_pk_bf16_f32 v233, v210, v211
	v_cvt_pk_bf16_f32 v234, v212, v213
	v_cvt_pk_bf16_f32 v235, v214, v215
	v_mul_f32_e32 v208, v208, v208
	v_mul_f32_e32 v209, v209, v209
	v_mul_f32_e32 v210, v210, v210
	v_mul_f32_e32 v211, v211, v211
	v_mul_f32_e32 v212, v212, v212
	v_mul_f32_e32 v213, v213, v213
	v_mul_f32_e32 v214, v214, v214
	v_mul_f32_e32 v215, v215, v215
	v_add_f32_e32 v208, v208, v209
	v_add_f32_e32 v210, v210, v211
	v_add_f32_e32 v208, v208, v210
	v_add_f32_e32 v212, v212, v213
	v_add_f32_e32 v208, v208, v212
	v_add_f32_e32 v214, v214, v215
	v_add_f32_e32 v208, v208, v214
	v_add_f32_e32 v2, v2, v208
	s_waitcnt lgkmcnt(0)
	v_mfma_f32_16x16x32_bf16 v[6:9], v[232:235], v[22:25], v[6:9]
	s_waitcnt vmcnt(10)
	ds_read_b128 v[14:17], v34 offset:30720
	v_cvt_pk_bf16_f32 v236, v216, v217
	v_cvt_pk_bf16_f32 v237, v218, v219
	v_cvt_pk_bf16_f32 v238, v220, v221
	v_cvt_pk_bf16_f32 v239, v222, v223
	v_mul_f32_e32 v216, v216, v216
	v_mul_f32_e32 v217, v217, v217
	v_mul_f32_e32 v218, v218, v218
	v_mul_f32_e32 v219, v219, v219
	v_mul_f32_e32 v220, v220, v220
	v_mul_f32_e32 v221, v221, v221
	v_mul_f32_e32 v222, v222, v222
	v_mul_f32_e32 v223, v223, v223
	v_add_f32_e32 v216, v216, v217
	v_add_f32_e32 v218, v218, v219
	v_add_f32_e32 v216, v216, v218
	v_add_f32_e32 v220, v220, v221
	v_add_f32_e32 v216, v216, v220
	v_add_f32_e32 v222, v222, v223
	v_add_f32_e32 v216, v216, v222
	v_add_f32_e32 v2, v2, v216
	s_waitcnt lgkmcnt(0)
	v_mfma_f32_16x16x32_bf16 v[6:9], v[236:239], v[14:17], v[6:9]
	s_waitcnt vmcnt(8)
	ds_read_b128 v[22:25], v34 offset:31744
	v_cvt_pk_bf16_f32 v240, v224, v225
	v_cvt_pk_bf16_f32 v241, v226, v227
	v_cvt_pk_bf16_f32 v242, v228, v229
	v_cvt_pk_bf16_f32 v243, v230, v231
	v_mul_f32_e32 v224, v224, v224
	v_mul_f32_e32 v225, v225, v225
	v_mul_f32_e32 v226, v226, v226
	v_mul_f32_e32 v227, v227, v227
	v_mul_f32_e32 v228, v228, v228
	v_mul_f32_e32 v229, v229, v229
	v_mul_f32_e32 v230, v230, v230
	v_mul_f32_e32 v231, v231, v231
	v_add_f32_e32 v224, v224, v225
	v_add_f32_e32 v226, v226, v227
	v_add_f32_e32 v224, v224, v226
	v_add_f32_e32 v228, v228, v229
	v_add_f32_e32 v224, v224, v228
	v_add_f32_e32 v230, v230, v231
	v_add_f32_e32 v224, v224, v230
	v_add_f32_e32 v2, v2, v224
	s_waitcnt lgkmcnt(0)
	v_mfma_f32_16x16x32_bf16 v[6:9], v[240:243], v[22:25], v[6:9]
	global_store_dwordx4 v[70:71], v[36:39], off offset:-128
	global_store_dwordx4 v[70:71], v[40:43], off offset:-64
	global_store_dwordx4 v[70:71], v[44:47], off
	global_store_dwordx4 v[70:71], v[48:51], off offset:64
	global_store_dwordx4 v[70:71], v[52:55], off offset:128
	global_store_dwordx4 v[70:71], v[232:235], off offset:192
	global_store_dwordx4 v[70:71], v[236:239], off offset:256
	global_store_dwordx4 v[70:71], v[240:243], off offset:320
	s_nop 7
	s_andn2_b64 vcc, exec, s[18:19]
	v_add_u32_e32 v12, 0x3000, v92
	v_add_u32_e32 v4, 0x3008, v92
	s_cbranch_vccnz .LBB0_13
	s_nop 2
	ds_write2_b32 v12, v6, v7 offset1:1
	ds_write2_b32 v4, v8, v9 offset1:1
	ds_write_b32 v92, v2 offset:12304
